# v117 + P11 final epilogue: the 8 row sums and 4 norm-weight chunks loaded once at the top of the normalisation part instead of per block behind full waits
# baseline (speedup 1.0000x reference)
.LBB0_1477:
	global_load_dword v202, v[112:113], off sc1
	global_load_dword v203, v[112:113], off offset:64 sc1
	global_load_dword v204, v[112:113], off offset:128 sc1
	global_load_dword v205, v[112:113], off offset:192 sc1
	global_load_dword v206, v[112:113], off offset:512 sc1
	global_load_dword v207, v[112:113], off offset:576 sc1
	global_load_dword v208, v[112:113], off offset:640 sc1
	global_load_dword v209, v[112:113], off offset:704 sc1
	v_lshlrev_b64 v[160:161], 2, v[142:143]
	v_lshl_add_u64 v[142:143], s[80:81], 0, v[160:161]
	s_waitcnt lgkmcnt(0)
	global_load_dwordx4 v[186:189], v[142:143], off
	global_load_dwordx4 v[190:193], v[142:143], off offset:16
	global_load_dwordx4 v[194:197], v[142:143], off offset:512
	global_load_dwordx4 v[198:201], v[142:143], off offset:528
	s_nop 0
	v_lshlrev_b64 v[140:141], 13, v[140:141]
	v_lshl_add_u64 v[140:141], s[82:83], 0, v[140:141]
	v_lshl_add_u64 v[140:141], v[140:141], 0, v[160:161]
	v_lshlrev_b64 v[122:123], 13, v[122:123]
	v_lshl_add_u64 v[122:123], s[82:83], 0, v[122:123]
	v_lshl_add_u64 v[122:123], v[122:123], 0, v[160:161]
	v_lshlrev_b64 v[104:105], 13, v[104:105]
	v_lshl_add_u64 v[104:105], s[82:83], 0, v[104:105]
	v_lshl_add_u64 v[104:105], v[104:105], 0, v[160:161]
	v_lshlrev_b64 v[88:89], 13, v[88:89]
	v_lshl_add_u64 v[88:89], s[82:83], 0, v[88:89]
	v_lshl_add_u64 v[88:89], v[88:89], 0, v[160:161]
	v_lshlrev_b64 v[72:73], 13, v[72:73]
	v_lshl_add_u64 v[72:73], s[82:83], 0, v[72:73]
	v_lshl_add_u64 v[72:73], v[72:73], 0, v[160:161]
	v_lshlrev_b64 v[56:57], 13, v[56:57]
	v_lshl_add_u64 v[56:57], s[82:83], 0, v[56:57]
	v_lshl_add_u64 v[56:57], v[56:57], 0, v[160:161]
	v_lshlrev_b64 v[40:41], 13, v[40:41]
	v_lshl_add_u64 v[40:41], s[82:83], 0, v[40:41]
	v_lshl_add_u64 v[40:41], v[40:41], 0, v[160:161]
	v_lshlrev_b64 v[24:25], 13, v[24:25]
	v_lshl_add_u64 v[24:25], s[82:83], 0, v[24:25]
	v_lshl_add_u64 v[24:25], v[24:25], 0, v[160:161]
	s_mov_b64 s[0:1], -1
	s_waitcnt vmcnt(11)
	v_fmamk_f32 v180, v202, 0x3a000000, v171
	v_mul_f32_e32 v181, 0x4b800000, v180
	v_cmp_gt_f32_e32 vcc, s44, v180
	s_nop 1
	v_cndmask_b32_e32 v180, v180, v181, vcc
	v_rsq_f32_e32 v180, v180
	s_nop 0
	v_mul_f32_e32 v181, 0x45800000, v180
	v_cndmask_b32_e32 v180, v180, v181, vcc
	v_pk_mul_f32 v[146:147], v[146:147], v[180:181] op_sel_hi:[1,0]
	v_pk_mul_f32 v[144:145], v[144:145], v[180:181] op_sel_hi:[1,0]
	v_pk_mul_f32 v[182:183], v[126:127], v[180:181] op_sel_hi:[1,0]
	v_pk_mul_f32 v[184:185], v[124:125], v[180:181] op_sel_hi:[1,0]
	s_waitcnt vmcnt(3)
	v_pk_mul_f32 v[126:127], v[188:189], v[144:145]
	v_pk_mul_f32 v[124:125], v[186:187], v[146:147]
	s_waitcnt vmcnt(2)
	v_pk_mul_f32 v[146:147], v[192:193], v[184:185]
	v_pk_mul_f32 v[144:145], v[190:191], v[182:183]
	global_store_dwordx4 v[140:141], v[124:127], off
	global_store_dwordx4 v[140:141], v[144:147], off offset:16
	s_nop 0
	s_nop 0
	s_nop 0
	v_pk_mul_f32 v[118:119], v[118:119], v[180:181] op_sel_hi:[1,0]
	v_pk_mul_f32 v[120:121], v[120:121], v[180:181] op_sel_hi:[1,0]
	v_pk_mul_f32 v[172:173], v[114:115], v[180:181] op_sel_hi:[1,0]
	v_pk_mul_f32 v[174:175], v[116:117], v[180:181] op_sel_hi:[1,0]
	s_waitcnt vmcnt(3)
	v_pk_mul_f32 v[114:115], v[194:195], v[120:121]
	v_pk_mul_f32 v[116:117], v[196:197], v[118:119]
	s_waitcnt vmcnt(2)
	v_pk_mul_f32 v[118:119], v[198:199], v[174:175]
	v_pk_mul_f32 v[120:121], v[200:201], v[172:173]
	global_store_dwordx4 v[140:141], v[114:117], off offset:512
	global_store_dwordx4 v[140:141], v[118:121], off offset:528
	s_nop 0
	s_nop 0
	s_nop 0
	s_nop 0
	s_nop 0
	v_fmamk_f32 v124, v203, 0x3a000000, v171
	v_mul_f32_e32 v125, 0x4b800000, v124
	v_cmp_gt_f32_e32 vcc, s44, v124
	s_nop 1
	v_cndmask_b32_e32 v124, v124, v125, vcc
	v_rsq_f32_e32 v124, v124
	s_nop 0
	v_mul_f32_e32 v125, 0x45800000, v124
	v_cndmask_b32_e32 v124, v124, v125, vcc
	v_pk_mul_f32 v[126:127], v[148:149], v[124:125] op_sel_hi:[1,0]
	v_pk_mul_f32 v[110:111], v[110:111], v[124:125] op_sel_hi:[1,0]
	v_pk_mul_f32 v[140:141], v[108:109], v[124:125] op_sel_hi:[1,0]
	v_pk_mul_f32 v[144:145], v[106:107], v[124:125] op_sel_hi:[1,0]
	s_nop 0
	v_pk_mul_f32 v[108:109], v[188:189], v[110:111]
	v_pk_mul_f32 v[106:107], v[186:187], v[126:127]
	s_nop 0
	v_pk_mul_f32 v[116:117], v[192:193], v[144:145]
	v_pk_mul_f32 v[114:115], v[190:191], v[140:141]
	global_store_dwordx4 v[122:123], v[106:109], off
	global_store_dwordx4 v[122:123], v[114:117], off offset:16
	s_nop 0
	s_nop 0
	s_nop 0
	v_pk_mul_f32 v[102:103], v[102:103], v[124:125] op_sel_hi:[1,0]
	v_pk_mul_f32 v[100:101], v[100:101], v[124:125] op_sel_hi:[1,0]
	v_pk_mul_f32 v[110:111], v[98:99], v[124:125] op_sel_hi:[1,0]
	v_pk_mul_f32 v[118:119], v[96:97], v[124:125] op_sel_hi:[1,0]
	s_nop 0
	v_pk_mul_f32 v[96:97], v[194:195], v[100:101]
	v_pk_mul_f32 v[98:99], v[196:197], v[102:103]
	s_nop 0
	v_pk_mul_f32 v[100:101], v[198:199], v[118:119]
	v_pk_mul_f32 v[102:103], v[200:201], v[110:111]
	global_store_dwordx4 v[122:123], v[96:99], off offset:512
	global_store_dwordx4 v[122:123], v[100:103], off offset:528
	s_nop 0
	s_nop 0
	s_nop 0
	s_nop 0
	s_nop 0
	v_fmamk_f32 v106, v204, 0x3a000000, v171
	v_mul_f32_e32 v107, 0x4b800000, v106
	v_cmp_gt_f32_e32 vcc, s44, v106
	s_nop 1
	v_cndmask_b32_e32 v106, v106, v107, vcc
	v_rsq_f32_e32 v106, v106
	s_nop 0
	v_mul_f32_e32 v107, 0x45800000, v106
	v_cndmask_b32_e32 v106, v106, v107, vcc
	v_pk_mul_f32 v[108:109], v[150:151], v[106:107] op_sel_hi:[1,0]
	v_pk_mul_f32 v[94:95], v[94:95], v[106:107] op_sel_hi:[1,0]
	v_pk_mul_f32 v[110:111], v[92:93], v[106:107] op_sel_hi:[1,0]
	v_pk_mul_f32 v[114:115], v[90:91], v[106:107] op_sel_hi:[1,0]
	s_nop 0
	v_pk_mul_f32 v[92:93], v[188:189], v[94:95]
	v_pk_mul_f32 v[90:91], v[186:187], v[108:109]
	s_nop 0
	v_pk_mul_f32 v[96:97], v[192:193], v[114:115]
	v_pk_mul_f32 v[94:95], v[190:191], v[110:111]
	global_store_dwordx4 v[104:105], v[90:93], off
	global_store_dwordx4 v[104:105], v[94:97], off offset:16
	s_nop 0
	s_nop 0
	s_nop 0
	v_pk_mul_f32 v[86:87], v[86:87], v[106:107] op_sel_hi:[1,0]
	v_pk_mul_f32 v[84:85], v[84:85], v[106:107] op_sel_hi:[1,0]
	v_pk_mul_f32 v[98:99], v[82:83], v[106:107] op_sel_hi:[1,0]
	v_pk_mul_f32 v[100:101], v[80:81], v[106:107] op_sel_hi:[1,0]
	s_nop 0
	v_pk_mul_f32 v[80:81], v[194:195], v[84:85]
	v_pk_mul_f32 v[82:83], v[196:197], v[86:87]
	s_nop 0
	v_pk_mul_f32 v[84:85], v[198:199], v[100:101]
	v_pk_mul_f32 v[86:87], v[200:201], v[98:99]
	global_store_dwordx4 v[104:105], v[80:83], off offset:512
	global_store_dwordx4 v[104:105], v[84:87], off offset:528
	s_nop 0
	s_nop 0
	s_nop 0
	s_nop 0
	s_nop 0
	v_fmamk_f32 v90, v205, 0x3a000000, v171
	v_mul_f32_e32 v91, 0x4b800000, v90
	v_cmp_gt_f32_e32 vcc, s44, v90
	s_nop 1
	v_cndmask_b32_e32 v90, v90, v91, vcc
	v_rsq_f32_e32 v90, v90
	s_nop 0
	v_mul_f32_e32 v91, 0x45800000, v90
	v_cndmask_b32_e32 v90, v90, v91, vcc
	v_pk_mul_f32 v[92:93], v[152:153], v[90:91] op_sel_hi:[1,0]
	v_pk_mul_f32 v[78:79], v[78:79], v[90:91] op_sel_hi:[1,0]
	v_pk_mul_f32 v[94:95], v[76:77], v[90:91] op_sel_hi:[1,0]
	v_pk_mul_f32 v[96:97], v[74:75], v[90:91] op_sel_hi:[1,0]
	s_nop 0
	v_pk_mul_f32 v[76:77], v[188:189], v[78:79]
	v_pk_mul_f32 v[74:75], v[186:187], v[92:93]
	s_nop 0
	v_pk_mul_f32 v[80:81], v[192:193], v[96:97]
	v_pk_mul_f32 v[78:79], v[190:191], v[94:95]
	global_store_dwordx4 v[88:89], v[74:77], off
	global_store_dwordx4 v[88:89], v[78:81], off offset:16
	s_nop 0
	s_nop 0
	s_nop 0
	v_pk_mul_f32 v[70:71], v[70:71], v[90:91] op_sel_hi:[1,0]
	v_pk_mul_f32 v[68:69], v[68:69], v[90:91] op_sel_hi:[1,0]
	v_pk_mul_f32 v[82:83], v[66:67], v[90:91] op_sel_hi:[1,0]
	v_pk_mul_f32 v[84:85], v[64:65], v[90:91] op_sel_hi:[1,0]
	s_nop 0
	v_pk_mul_f32 v[64:65], v[194:195], v[68:69]
	v_pk_mul_f32 v[66:67], v[196:197], v[70:71]
	s_nop 0
	v_pk_mul_f32 v[68:69], v[198:199], v[84:85]
	v_pk_mul_f32 v[70:71], v[200:201], v[82:83]
	global_store_dwordx4 v[88:89], v[64:67], off offset:512
	global_store_dwordx4 v[88:89], v[68:71], off offset:528
	s_nop 0
	s_nop 0
	s_nop 0
	s_nop 0
	s_nop 0
	v_fmamk_f32 v74, v206, 0x3a000000, v171
	v_mul_f32_e32 v75, 0x4b800000, v74
	v_cmp_gt_f32_e32 vcc, s44, v74
	s_nop 1
	v_cndmask_b32_e32 v74, v74, v75, vcc
	v_rsq_f32_e32 v74, v74
	s_nop 0
	v_mul_f32_e32 v75, 0x45800000, v74
	v_cndmask_b32_e32 v74, v74, v75, vcc
	v_pk_mul_f32 v[76:77], v[154:155], v[74:75] op_sel_hi:[1,0]
	v_pk_mul_f32 v[62:63], v[62:63], v[74:75] op_sel_hi:[1,0]
	v_pk_mul_f32 v[78:79], v[60:61], v[74:75] op_sel_hi:[1,0]
	v_pk_mul_f32 v[80:81], v[58:59], v[74:75] op_sel_hi:[1,0]
	s_nop 0
	v_pk_mul_f32 v[60:61], v[188:189], v[62:63]
	v_pk_mul_f32 v[58:59], v[186:187], v[76:77]
	s_nop 0
	v_pk_mul_f32 v[64:65], v[192:193], v[80:81]
	v_pk_mul_f32 v[62:63], v[190:191], v[78:79]
	global_store_dwordx4 v[72:73], v[58:61], off
	global_store_dwordx4 v[72:73], v[62:65], off offset:16
	s_nop 0
	s_nop 0
	s_nop 0
	v_pk_mul_f32 v[54:55], v[54:55], v[74:75] op_sel_hi:[1,0]
	v_pk_mul_f32 v[52:53], v[52:53], v[74:75] op_sel_hi:[1,0]
	v_pk_mul_f32 v[66:67], v[50:51], v[74:75] op_sel_hi:[1,0]
	v_pk_mul_f32 v[68:69], v[48:49], v[74:75] op_sel_hi:[1,0]
	s_nop 0
	v_pk_mul_f32 v[48:49], v[194:195], v[52:53]
	v_pk_mul_f32 v[50:51], v[196:197], v[54:55]
	s_nop 0
	v_pk_mul_f32 v[52:53], v[198:199], v[68:69]
	v_pk_mul_f32 v[54:55], v[200:201], v[66:67]
	global_store_dwordx4 v[72:73], v[48:51], off offset:512
	global_store_dwordx4 v[72:73], v[52:55], off offset:528
	s_nop 0
	s_nop 0
	s_nop 0
	s_nop 0
	s_nop 0
	v_fmamk_f32 v58, v207, 0x3a000000, v171
	v_mul_f32_e32 v59, 0x4b800000, v58
	v_cmp_gt_f32_e32 vcc, s44, v58
	s_nop 1
	v_cndmask_b32_e32 v58, v58, v59, vcc
	v_rsq_f32_e32 v58, v58
	s_nop 0
	v_mul_f32_e32 v59, 0x45800000, v58
	v_cndmask_b32_e32 v58, v58, v59, vcc
	v_pk_mul_f32 v[60:61], v[156:157], v[58:59] op_sel_hi:[1,0]
	v_pk_mul_f32 v[46:47], v[46:47], v[58:59] op_sel_hi:[1,0]
	v_pk_mul_f32 v[62:63], v[44:45], v[58:59] op_sel_hi:[1,0]
	v_pk_mul_f32 v[64:65], v[42:43], v[58:59] op_sel_hi:[1,0]
	s_nop 0
	v_pk_mul_f32 v[44:45], v[188:189], v[46:47]
	v_pk_mul_f32 v[42:43], v[186:187], v[60:61]
	s_nop 0
	v_pk_mul_f32 v[48:49], v[192:193], v[64:65]
	v_pk_mul_f32 v[46:47], v[190:191], v[62:63]
	global_store_dwordx4 v[56:57], v[42:45], off
	global_store_dwordx4 v[56:57], v[46:49], off offset:16
	s_nop 0
	s_nop 0
	s_nop 0
	v_pk_mul_f32 v[38:39], v[38:39], v[58:59] op_sel_hi:[1,0]
	v_pk_mul_f32 v[36:37], v[36:37], v[58:59] op_sel_hi:[1,0]
	v_pk_mul_f32 v[50:51], v[34:35], v[58:59] op_sel_hi:[1,0]
	v_pk_mul_f32 v[52:53], v[32:33], v[58:59] op_sel_hi:[1,0]
	s_nop 0
	v_pk_mul_f32 v[32:33], v[194:195], v[36:37]
	v_pk_mul_f32 v[34:35], v[196:197], v[38:39]
	s_nop 0
	v_pk_mul_f32 v[36:37], v[198:199], v[52:53]
	v_pk_mul_f32 v[38:39], v[200:201], v[50:51]
	global_store_dwordx4 v[56:57], v[32:35], off offset:512
	global_store_dwordx4 v[56:57], v[36:39], off offset:528
	s_nop 0
	s_nop 0
	s_nop 0
	s_nop 0
	s_nop 0
	v_fmamk_f32 v42, v208, 0x3a000000, v171
	v_mul_f32_e32 v43, 0x4b800000, v42
	v_cmp_gt_f32_e32 vcc, s44, v42
	s_nop 1
	v_cndmask_b32_e32 v42, v42, v43, vcc
	v_rsq_f32_e32 v42, v42
	s_nop 0
	v_mul_f32_e32 v43, 0x45800000, v42
	v_cndmask_b32_e32 v42, v42, v43, vcc
	v_pk_mul_f32 v[44:45], v[158:159], v[42:43] op_sel_hi:[1,0]
	v_pk_mul_f32 v[30:31], v[30:31], v[42:43] op_sel_hi:[1,0]
	v_pk_mul_f32 v[46:47], v[28:29], v[42:43] op_sel_hi:[1,0]
	v_pk_mul_f32 v[48:49], v[26:27], v[42:43] op_sel_hi:[1,0]
	s_nop 0
	v_pk_mul_f32 v[28:29], v[188:189], v[30:31]
	v_pk_mul_f32 v[26:27], v[186:187], v[44:45]
	s_nop 0
	v_pk_mul_f32 v[32:33], v[192:193], v[48:49]
	v_pk_mul_f32 v[30:31], v[190:191], v[46:47]
	global_store_dwordx4 v[40:41], v[26:29], off
	global_store_dwordx4 v[40:41], v[30:33], off offset:16
	s_nop 0
	s_nop 0
	s_nop 0
	v_pk_mul_f32 v[22:23], v[22:23], v[42:43] op_sel_hi:[1,0]
	v_pk_mul_f32 v[20:21], v[20:21], v[42:43] op_sel_hi:[1,0]
	v_pk_mul_f32 v[34:35], v[18:19], v[42:43] op_sel_hi:[1,0]
	v_pk_mul_f32 v[36:37], v[16:17], v[42:43] op_sel_hi:[1,0]
	s_nop 0
	v_pk_mul_f32 v[16:17], v[194:195], v[20:21]
	v_pk_mul_f32 v[18:19], v[196:197], v[22:23]
	s_nop 0
	v_pk_mul_f32 v[20:21], v[198:199], v[36:37]
	v_pk_mul_f32 v[22:23], v[200:201], v[34:35]
	global_store_dwordx4 v[40:41], v[16:19], off offset:512
	global_store_dwordx4 v[40:41], v[20:23], off offset:528
	s_nop 0
	s_nop 0
	s_nop 0
	s_nop 0
	s_nop 0
	v_fmamk_f32 v26, v209, 0x3a000000, v171
	v_mul_f32_e32 v27, 0x4b800000, v26
	v_cmp_gt_f32_e32 vcc, s44, v26
	s_nop 1
	v_cndmask_b32_e32 v26, v26, v27, vcc
	v_rsq_f32_e32 v26, v26
	s_nop 0
	v_mul_f32_e32 v27, 0x45800000, v26
	v_cndmask_b32_e32 v26, v26, v27, vcc
	v_pk_mul_f32 v[12:13], v[12:13], v[26:27] op_sel_hi:[1,0]
	v_pk_mul_f32 v[14:15], v[14:15], v[26:27] op_sel_hi:[1,0]
	v_pk_mul_f32 v[28:29], v[8:9], v[26:27] op_sel_hi:[1,0]
	v_pk_mul_f32 v[30:31], v[10:11], v[26:27] op_sel_hi:[1,0]
	s_nop 0
	v_pk_mul_f32 v[10:11], v[188:189], v[14:15]
	v_pk_mul_f32 v[8:9], v[186:187], v[12:13]
	s_nop 0
	v_pk_mul_f32 v[14:15], v[192:193], v[30:31]
	v_pk_mul_f32 v[12:13], v[190:191], v[28:29]
	global_store_dwordx4 v[24:25], v[8:11], off
	global_store_dwordx4 v[24:25], v[12:15], off offset:16
	s_nop 0
	s_nop 0
	s_nop 0
	v_pk_mul_f32 v[6:7], v[6:7], v[26:27] op_sel_hi:[1,0]
	v_pk_mul_f32 v[4:5], v[4:5], v[26:27] op_sel_hi:[1,0]
	s_andn2_b64 vcc, exec, s[18:19]
	v_pk_mul_f32 v[16:17], v[2:3], v[26:27] op_sel_hi:[1,0]
	v_pk_mul_f32 v[18:19], v[0:1], v[26:27] op_sel_hi:[1,0]
	s_nop 0
	v_pk_mul_f32 v[0:1], v[194:195], v[4:5]
	v_pk_mul_f32 v[2:3], v[196:197], v[6:7]
	s_nop 0
	v_pk_mul_f32 v[4:5], v[198:199], v[18:19]
	v_pk_mul_f32 v[6:7], v[200:201], v[16:17]
	global_store_dwordx4 v[24:25], v[0:3], off offset:512
	global_store_dwordx4 v[24:25], v[4:7], off offset:528
	s_cbranch_vccnz .LBB0_1433
	s_andn2_b64 vcc, exec, s[4:5]
	s_cbranch_vccnz .LBB0_1432
	s_barrier
	s_branch .LBB0_1432
